# prologue SSM-table loop: the 16 serial (b_re,b_im) load pairs per thread issued together, so the first workgroups reach the first grid sync earlier
# baseline (speedup 1.0000x reference)
; #define ABAR WSF(WS_ABAR)
; #define BB WSF(WS_BB)
; #define ABAR WSF(WS_ABAR)
; DI void prologue(PP p, LAS unsigned char* lds) {
;     ...
;         for (int i = gt; i < 4 * 32 * 64; i += NGT) {
;             const int lg = i >> 6;
;             const float lre = fminf(a_re[i], -1e-4f), lim = a_im[i];
;             const float dt = __expf(log_dt[lg]);
;             const double xr = (double)lre * (double)dt, th = (double)lim * (double)dt;
;             double rev = th * 0.15915494309189535; rev -= rint(rev);
;             const float r = (float)(rev * 6.283185307179586);
;             float sn, cs; sincosf(r, &sn, &cs);
;             const float ex = __expf((float)xr), em1 = expm1f((float)xr);
;             ABAR[2 * i] = ex * cs; ABAR[2 * i + 1] = ex * sn;
;             { double rev2 = th * 64.0 * 0.15915494309189535; rev2 -= rint(rev2); float s2, c2; sincosf((float)(rev2 * 6.283185307179586), &s2, &c2);
;               const float e2 = __expf((float)(xr * 64.0)); A64[2 * i] = e2 * c2; A64[2 * i + 1] = e2 * s2; }
;             float sh, ch; sincosf(0.5f * r, &sh, &ch);
;             const float dre = em1 * cs - 2.f * sh * sh, dim = ex * sn;
;             const float den = 1.f / (lre * lre + lim * lim);
;             const float qre = (dre * lre + dim * lim) * den, qim = (dim * lre - dre * lim) * den;
;             for (int pp = 0; pp < 16; ++pp) {
;                 const float br = b_re[(size_t)i * 16 + pp], bi = b_im[(size_t)i * 16 + pp];
;                 BB[((size_t)i * 16 + pp) * 2] = qre * br - qim * bi; BB[((size_t)i * 16 + pp) * 2 + 1] = qre * bi + qim * br;
.LBB0_22:
	s_or_b64 exec, exec, s[6:7]
	v_lshl_add_u64 v[26:27], s[18:19], 0, v[8:9]
	v_lshl_add_u64 v[24:25], s[16:17], 0, v[8:9]
	global_load_dword v42, v[26:27], off
	global_load_dword v44, v[24:25], off
	global_load_dword v109, v[26:27], off offset:4
	global_load_dword v110, v[24:25], off offset:4
	global_load_dword v111, v[26:27], off offset:8
	global_load_dword v112, v[24:25], off offset:8
	global_load_dword v113, v[26:27], off offset:12
	global_load_dword v114, v[24:25], off offset:12
	global_load_dword v115, v[26:27], off offset:16
	global_load_dword v116, v[24:25], off offset:16
	global_load_dword v117, v[26:27], off offset:20
	global_load_dword v118, v[24:25], off offset:20
	global_load_dword v119, v[26:27], off offset:24
	global_load_dword v120, v[24:25], off offset:24
	global_load_dword v121, v[26:27], off offset:28
	global_load_dword v122, v[24:25], off offset:28
	global_load_dword v123, v[26:27], off offset:32
	global_load_dword v124, v[24:25], off offset:32
	global_load_dword v125, v[26:27], off offset:36
	global_load_dword v126, v[24:25], off offset:36
	global_load_dword v127, v[26:27], off offset:40
	global_load_dword v128, v[24:25], off offset:40
	global_load_dword v129, v[26:27], off offset:44
	global_load_dword v130, v[24:25], off offset:44
	global_load_dword v131, v[26:27], off offset:48
	global_load_dword v132, v[24:25], off offset:48
	global_load_dword v133, v[26:27], off offset:52
	global_load_dword v134, v[24:25], off offset:52
	global_load_dword v135, v[26:27], off offset:56
	global_load_dword v136, v[24:25], off offset:56
	global_load_dword v137, v[26:27], off offset:60
	global_load_dword v138, v[24:25], off offset:60
	v_rndne_f32_e32 v21, v21
	v_lshlrev_b32_e32 v45, 30, v41
	v_pk_mul_f32 v[46:47], v[16:17], v[16:17]
	v_mul_f32_e32 v43, v12, v12
	v_xor_b32_e32 v51, v22, v5
	v_fmac_f32_e32 v40, 0xbf317218, v21
	v_and_b32_e32 v45, 0x80000000, v45
	v_add_f32_e32 v46, v46, v47
	v_mov_b32_e32 v49, v16
	v_mov_b32_e32 v16, v23
	v_mov_b32_e32 v50, v23
	v_fmamk_f32 v23, v43, 0xb94c1982, v31
	v_fmamk_f32 v52, v43, 0x37d75334, v32
	v_fmac_f32_e32 v40, 0x3102e308, v21
	v_xor_b32_e32 v45, v51, v45
	v_div_scale_f32 v51, s[6:7], v46, v46, 1.0
	v_mov_b32_e32 v22, v17
	v_mov_b32_e32 v48, v17
	v_cvt_i32_f32_e32 v17, v21
	v_fmaak_f32 v23, v43, v23, 0xbe2aaa9d
	v_fmaak_f32 v47, v43, v52, 0x3d2aabf7
	v_fmamk_f32 v53, v40, 0x395133b1, v33
	v_rcp_f32_e32 v54, v51
	v_and_b32_e32 v41, 1, v41
	v_mul_f32_e32 v23, v43, v23
	v_fmaak_f32 v47, v43, v47, 0xbf000004
	v_fmaak_f32 v53, v40, v53, 0x3c0887f9
	v_fmac_f32_e32 v12, v12, v23
	v_fma_f32 v23, v43, v47, 1.0
	v_fmaak_f32 v43, v40, v53, 0x3d2aaa81
	v_cmp_eq_u32_e64 s[6:7], 0, v41
	v_ldexp_f32 v17, 1.0, v17
	v_cmp_class_f32_e64 s[8:9], v5, s73
	v_cndmask_b32_e64 v12, v23, v12, s[6:7]
	v_fmaak_f32 v23, v40, v43, 0x3e2aaaab
	v_cmp_eq_f32_e64 s[6:7], s74, v21
	v_xor_b32_e32 v12, v45, v12
	v_fma_f32 v21, v40, v23, 0.5
	v_fma_f32 v5, -v51, v54, 1.0
	v_div_scale_f32 v52, vcc, 1.0, v46, 1.0
	v_cndmask_b32_e64 v17, v17, v37, s[6:7]
	v_cndmask_b32_e64 v41, v36, v12, s[8:9]
	v_mul_f32_e32 v12, v40, v21
	v_fmac_f32_e32 v54, v5, v54
	v_add_f32_e32 v23, -1.0, v17
	v_fmac_f32_e32 v40, v40, v12
	v_mul_f32_e32 v5, v52, v54
	v_fmac_f32_e32 v23, v17, v40
	v_fma_f32 v12, -v51, v5, v52
	v_add_f32_e32 v17, v23, v23
	v_fmac_f32_e32 v5, v12, v54
	v_cndmask_b32_e64 v12, v23, v17, s[6:7]
	v_fma_f32 v17, -v51, v5, v52
	v_cmp_nlt_f64_e64 s[6:7], s[54:55], v[18:19]
	v_div_fmas_f32 v5, v17, v54, v5
	v_cmp_ngt_f64_e32 vcc, s[56:57], v[18:19]
	v_cndmask_b32_e64 v12, v38, v12, s[6:7]
	v_add_f32_e32 v21, v41, v41
	v_cndmask_b32_e32 v40, -1.0, v12, vcc
	v_pk_mul_f32 v[18:19], v[40:41], v[20:21]
	v_div_fixup_f32 v12, v5, v46, 1.0
	v_pk_add_f32 v[18:19], v[18:19], v[18:19] op_sel:[0,1] op_sel_hi:[0,1] neg_lo:[0,1] neg_hi:[0,1]
	v_pk_mul_f32 v[18:19], v[48:49], v[18:19] op_sel:[1,0] op_sel_hi:[0,1]
	v_pk_fma_f32 v[16:17], v[22:23], v[16:17], v[18:19]
	v_pk_fma_f32 v[18:19], v[48:49], v[50:51], v[18:19] op_sel_hi:[1,0,1] neg_lo:[0,0,1] neg_hi:[0,0,1]
	s_add_u32 s18, s18, s44
	v_mov_b32_e32 v17, v19
	v_pk_mul_f32 v[16:17], v[12:13], v[16:17] op_sel_hi:[0,1]
	v_lshlrev_b64 v[14:15], 12, v[14:15]
	s_addc_u32 s19, s19, s45
	v_add_u32_e32 v39, s4, v39
	v_lshl_add_u64 v[14:15], s[40:41], 0, v[14:15]
	s_add_u32 s16, s16, s44
	v_cmp_lt_i32_e32 vcc, s75, v39
	s_addc_u32 s17, s17, s45
	v_add_u32_e32 v4, s60, v4
	s_waitcnt vmcnt(31)
	v_pk_mul_f32 v[18:19], v[42:43], v[16:17] op_sel:[0,1] op_sel_hi:[0,0]
	s_waitcnt vmcnt(30)
	v_pk_fma_f32 v[20:21], v[44:45], v[16:17], v[18:19] op_sel_hi:[0,1,1] neg_lo:[0,0,1] neg_hi:[0,0,1]
	v_pk_fma_f32 v[18:19], v[44:45], v[16:17], v[18:19] op_sel_hi:[0,1,1]
	v_mov_b32_e32 v21, v19
	global_store_dwordx2 v[6:7], v[20:21], off
	s_or_b64 s[48:49], vcc, s[48:49]
	v_lshl_add_u64 v[10:11], v[10:11], 0, s[46:47]
	s_waitcnt vmcnt(29)
	v_mov_b32_e32 v12, v109
	v_mov_b32_e32 v18, v110
	v_pk_mul_f32 v[22:23], v[12:13], v[16:17] op_sel:[0,1] op_sel_hi:[0,0]
	v_pk_fma_f32 v[40:41], v[18:19], v[16:17], v[22:23] op_sel_hi:[0,1,1] neg_lo:[0,0,1] neg_hi:[0,0,1]
	v_pk_fma_f32 v[22:23], v[18:19], v[16:17], v[22:23] op_sel_hi:[0,1,1]
	v_mov_b32_e32 v41, v23
	global_store_dwordx2 v[6:7], v[40:41], off offset:8
	v_cvt_pk_bf16_f32 v22, v19, v23
	s_waitcnt vmcnt(28)
	v_mov_b32_e32 v12, v111
	v_mov_b32_e32 v18, v112
	v_pk_mul_f32 v[42:43], v[12:13], v[16:17] op_sel:[0,1] op_sel_hi:[0,0]
	v_pk_fma_f32 v[44:45], v[18:19], v[16:17], v[42:43] op_sel_hi:[0,1,1] neg_lo:[0,0,1] neg_hi:[0,0,1]
	v_pk_fma_f32 v[42:43], v[18:19], v[16:17], v[42:43] op_sel_hi:[0,1,1]
	v_mov_b32_e32 v45, v43
	global_store_dwordx2 v[6:7], v[44:45], off offset:16
	s_waitcnt vmcnt(27)
; DI unsigned cvtpk(float lo, float hi) { f32x2 v = {lo, hi}; bf16x2_t b = __builtin_convertvector(v, bf16x2_t); return __builtin_bit_cast(unsigned, b); }
; #define BB WSF(WS_BB)
; DI void prologue(PP p, LAS unsigned char* lds) {
;     ...
;             for (int pp = 0; pp < 16; ++pp) {
;                 const float br = b_re[(size_t)i * 16 + pp], bi = b_im[(size_t)i * 16 + pp];
;                 BB[((size_t)i * 16 + pp) * 2] = qre * br - qim * bi; BB[((size_t)i * 16 + pp) * 2 + 1] = qre * bi + qim * br;
;                 { bf16_t* BBb = (bf16_t*)(ws + WS_BBB); const int n = i & 63;
;                   BBb[((size_t)lg * 128 + 2 * n) * 16 + pp] = (bf16_t)(cvtpk(qre * br - qim * bi, 0.f) & 0xffffu);
;                   BBb[((size_t)lg * 128 + 2 * n + 1) * 16 + pp] = (bf16_t)(cvtpk(qre * bi + qim * br, 0.f) & 0xffffu); }
;             }
	v_mov_b32_e32 v12, v113
	v_mov_b32_e32 v18, v114
	v_pk_mul_f32 v[46:47], v[16:17], v[12:13] op_sel:[1,0] op_sel_hi:[0,0]
	v_pk_fma_f32 v[48:49], v[16:17], v[18:19], v[46:47] op_sel_hi:[1,0,1] neg_lo:[0,0,1] neg_hi:[0,0,1]
	v_pk_fma_f32 v[46:47], v[16:17], v[18:19], v[46:47] op_sel_hi:[1,0,1]
	s_nop 0
	v_mov_b32_e32 v49, v47
	global_store_dwordx2 v[6:7], v[48:49], off offset:24
	v_cvt_pk_bf16_f32 v23, v43, v47
	s_waitcnt vmcnt(26)
	v_mov_b32_e32 v12, v115
	v_mov_b32_e32 v18, v116
	v_pk_mul_f32 v[50:51], v[16:17], v[12:13] op_sel:[1,0] op_sel_hi:[0,0]
	v_pk_fma_f32 v[52:53], v[16:17], v[18:19], v[50:51] op_sel_hi:[1,0,1] neg_lo:[0,0,1] neg_hi:[0,0,1]
	v_pk_fma_f32 v[50:51], v[16:17], v[18:19], v[50:51] op_sel_hi:[1,0,1]
	s_nop 0
	v_mov_b32_e32 v53, v51
	global_store_dwordx2 v[6:7], v[52:53], off offset:32
	s_waitcnt vmcnt(25)
	v_mov_b32_e32 v12, v117
	v_mov_b32_e32 v18, v118
	v_pk_mul_f32 v[54:55], v[16:17], v[12:13] op_sel:[1,0] op_sel_hi:[0,0]
	v_pk_fma_f32 v[56:57], v[16:17], v[18:19], v[54:55] op_sel_hi:[1,0,1] neg_lo:[0,0,1] neg_hi:[0,0,1]
	v_pk_fma_f32 v[54:55], v[16:17], v[18:19], v[54:55] op_sel_hi:[1,0,1]
	s_nop 0
	v_mov_b32_e32 v57, v55
	global_store_dwordx2 v[6:7], v[56:57], off offset:40
	s_waitcnt vmcnt(24)
	v_mov_b32_e32 v12, v119
	v_mov_b32_e32 v18, v120
	v_pk_mul_f32 v[58:59], v[16:17], v[12:13] op_sel:[1,0] op_sel_hi:[0,0]
	v_pk_fma_f32 v[60:61], v[16:17], v[18:19], v[58:59] op_sel_hi:[1,0,1] neg_lo:[0,0,1] neg_hi:[0,0,1]
	v_pk_fma_f32 v[58:59], v[16:17], v[18:19], v[58:59] op_sel_hi:[1,0,1]
	s_nop 0
	v_mov_b32_e32 v61, v59
	global_store_dwordx2 v[6:7], v[60:61], off offset:48
	s_waitcnt vmcnt(23)
	v_mov_b32_e32 v12, v121
	v_mov_b32_e32 v18, v122
	v_pk_mul_f32 v[62:63], v[16:17], v[12:13] op_sel:[1,0] op_sel_hi:[0,0]
	v_pk_fma_f32 v[64:65], v[16:17], v[18:19], v[62:63] op_sel_hi:[1,0,1] neg_lo:[0,0,1] neg_hi:[0,0,1]
	v_pk_fma_f32 v[62:63], v[16:17], v[18:19], v[62:63] op_sel_hi:[1,0,1]
	v_cvt_pk_bf16_f32 v21, v60, v64
	v_mov_b32_e32 v65, v63
	global_store_dwordx2 v[6:7], v[64:65], off offset:56
	s_waitcnt vmcnt(22)
	v_mov_b32_e32 v12, v123
	v_mov_b32_e32 v18, v124
	v_pk_mul_f32 v[66:67], v[16:17], v[12:13] op_sel:[1,0] op_sel_hi:[0,0]
	v_pk_fma_f32 v[68:69], v[16:17], v[18:19], v[66:67] op_sel_hi:[1,0,1] neg_lo:[0,0,1] neg_hi:[0,0,1]
	v_pk_fma_f32 v[66:67], v[16:17], v[18:19], v[66:67] op_sel_hi:[1,0,1]
	s_nop 0
	v_mov_b32_e32 v69, v67
	global_store_dwordx2 v[6:7], v[68:69], off offset:64
	s_waitcnt vmcnt(21)
	v_mov_b32_e32 v12, v125
	v_mov_b32_e32 v18, v126
	v_pk_mul_f32 v[70:71], v[16:17], v[12:13] op_sel:[1,0] op_sel_hi:[0,0]
	v_pk_fma_f32 v[72:73], v[16:17], v[18:19], v[70:71] op_sel_hi:[1,0,1] neg_lo:[0,0,1] neg_hi:[0,0,1]
	v_pk_fma_f32 v[70:71], v[16:17], v[18:19], v[70:71] op_sel_hi:[1,0,1]
	s_nop 0
	v_mov_b32_e32 v73, v71
	global_store_dwordx2 v[6:7], v[72:73], off offset:72
	s_waitcnt vmcnt(20)
	v_mov_b32_e32 v12, v127
	v_mov_b32_e32 v18, v128
	v_pk_mul_f32 v[74:75], v[16:17], v[12:13] op_sel:[1,0] op_sel_hi:[0,0]
	v_pk_fma_f32 v[76:77], v[16:17], v[18:19], v[74:75] op_sel_hi:[1,0,1] neg_lo:[0,0,1] neg_hi:[0,0,1]
	v_pk_fma_f32 v[74:75], v[16:17], v[18:19], v[74:75] op_sel_hi:[1,0,1]
	s_nop 0
	v_mov_b32_e32 v77, v75
	global_store_dwordx2 v[6:7], v[76:77], off offset:80
	s_waitcnt vmcnt(19)
	v_mov_b32_e32 v12, v129
	v_mov_b32_e32 v18, v130
	v_pk_mul_f32 v[78:79], v[16:17], v[12:13] op_sel:[1,0] op_sel_hi:[0,0]
	v_pk_fma_f32 v[80:81], v[16:17], v[18:19], v[78:79] op_sel_hi:[1,0,1] neg_lo:[0,0,1] neg_hi:[0,0,1]
	v_pk_fma_f32 v[78:79], v[16:17], v[18:19], v[78:79] op_sel_hi:[1,0,1]
	s_nop 0
	v_mov_b32_e32 v81, v79
	global_store_dwordx2 v[6:7], v[80:81], off offset:88
	s_waitcnt vmcnt(18)
	v_mov_b32_e32 v12, v131
	v_mov_b32_e32 v18, v132
	v_pk_mul_f32 v[82:83], v[16:17], v[12:13] op_sel:[1,0] op_sel_hi:[0,0]
	v_pk_fma_f32 v[84:85], v[16:17], v[18:19], v[82:83] op_sel_hi:[1,0,1] neg_lo:[0,0,1] neg_hi:[0,0,1]
	v_pk_fma_f32 v[82:83], v[16:17], v[18:19], v[82:83] op_sel_hi:[1,0,1]
	s_nop 0
	v_mov_b32_e32 v85, v83
	global_store_dwordx2 v[6:7], v[84:85], off offset:96
	s_waitcnt vmcnt(17)
	v_mov_b32_e32 v12, v133
	v_mov_b32_e32 v18, v134
	v_pk_mul_f32 v[86:87], v[16:17], v[12:13] op_sel:[1,0] op_sel_hi:[0,0]
	v_pk_fma_f32 v[88:89], v[16:17], v[18:19], v[86:87] op_sel_hi:[1,0,1] neg_lo:[0,0,1] neg_hi:[0,0,1]
	v_pk_fma_f32 v[86:87], v[16:17], v[18:19], v[86:87] op_sel_hi:[1,0,1]
	s_nop 0
	v_mov_b32_e32 v89, v87
	global_store_dwordx2 v[6:7], v[88:89], off offset:104
	s_waitcnt vmcnt(16)
	v_mov_b32_e32 v12, v135
	v_mov_b32_e32 v18, v136
	v_pk_mul_f32 v[90:91], v[16:17], v[12:13] op_sel:[1,0] op_sel_hi:[0,0]
	v_pk_fma_f32 v[92:93], v[16:17], v[18:19], v[90:91] op_sel_hi:[1,0,1] neg_lo:[0,0,1] neg_hi:[0,0,1]
	v_pk_fma_f32 v[90:91], v[16:17], v[18:19], v[90:91] op_sel_hi:[1,0,1]
	v_and_b32_e32 v12, 0xfc0, v30
	v_mov_b32_e32 v93, v91
	global_store_dwordx2 v[6:7], v[92:93], off offset:112
	s_nop 0
	v_cvt_pk_bf16_f32 v18, v20, v40
	v_lshl_add_u64 v[14:15], v[14:15], 0, v[12:13]
	v_cvt_pk_bf16_f32 v19, v44, v48
	v_cvt_pk_bf16_f32 v20, v52, v56
	v_cvt_pk_bf16_f32 v24, v51, v55
	v_cvt_pk_bf16_f32 v25, v59, v63
	v_add_u32_e32 v30, s3, v30
	global_store_dwordx4 v[14:15], v[18:21], off
	global_store_dwordx4 v[14:15], v[22:25], off offset:32
	s_waitcnt vmcnt(17)
	v_mov_b32_e32 v26, v137
	v_mov_b32_e32 v42, v138
	v_pk_mul_f32 v[26:27], v[16:17], v[26:27] op_sel:[1,0] op_sel_hi:[0,0]
	v_pk_fma_f32 v[40:41], v[16:17], v[42:43], v[26:27] op_sel_hi:[1,0,1] neg_lo:[0,0,1] neg_hi:[0,0,1]
	v_pk_fma_f32 v[16:17], v[16:17], v[42:43], v[26:27] op_sel_hi:[1,0,1]
	v_cvt_pk_bf16_f32 v18, v68, v72
	v_mov_b32_e32 v41, v17
	v_cvt_pk_bf16_f32 v22, v67, v71
	v_cvt_pk_bf16_f32 v19, v76, v80
	v_cvt_pk_bf16_f32 v23, v75, v79
	v_cvt_pk_bf16_f32 v20, v84, v88
	v_cvt_pk_bf16_f32 v24, v83, v87
	v_cvt_pk_bf16_f32 v21, v92, v40
	v_cvt_pk_bf16_f32 v25, v91, v17
	global_store_dwordx2 v[6:7], v[40:41], off offset:120
	global_store_dwordx4 v[14:15], v[18:21], off offset:16
	global_store_dwordx4 v[14:15], v[22:25], off offset:48
	v_lshl_add_u64 v[6:7], v[6:7], 0, s[42:43]
	s_andn2_b64 exec, exec, s[48:49]
	s_cbranch_execz .LBB0_35
